# v17 + nt hint on LayerNorm row loads (read-once f32 rows)
# baseline (speedup 1.0000x reference)
; #define PH_BEGIN const Params P = load_params(); unsigned char* ws = P.ws;
; __device__ __forceinline__ void ln_load(f32x4 (&v)[8], const float* z, int lane) {
; #pragma unroll
;     for (int j = 0; j < 8; ++j) v[j] = ((const f32x4*)z)[lane + 64 * j];
; }
; template <int L, int K>
; __device__ __forceinline__ void phase_body(char* lds, int rep_) {
;     ...
;     if constexpr (K == 5) { PH_BEGIN
;         const float* g1 = P.in[11] + L * DM; const float* b1 = P.in[12] + L * DM; const float* Z1 = (const float*)(ws + WS_Z1); bf16_t* HB = (bf16_t*)(ws + WS_HB);
;         const float* lg_ = g1; const float* lb_ = b1;
;     ...
;         LN_ROWS(gw, LTOK, NGW, ZR_, HR_, FR_);
.LBB0_1194:
	s_cmp_lt_i32 s80, 7
	s_cselect_b64 s[6:7], -1, 0
	s_cmp_gt_i32 s81, 6
	s_cselect_b64 s[8:9], -1, 0
	s_and_b64 s[6:7], s[6:7], s[8:9]
	s_andn2_b64 vcc, exec, s[6:7]
	s_cbranch_vccnz .LBB0_1204
	v_mov_b32_e32 v1, v194
	s_lshl_b32 s6, s2, 3
	v_readfirstlane_b32 s3, v1
	s_ashr_i32 s3, s3, 6
	s_add_i32 s6, s3, s6
	s_mov_b64 s[16:17], s[0:1]
	s_cmpk_gt_i32 s6, 0x400f
	s_cbranch_scc1 .LBB0_1204
	s_load_dword s3, s[0:1], 0xa0
	s_load_dwordx2 s[12:13], s[16:17], 0x90
	v_and_b32_e32 v86, 63, v1
	v_lshlrev_b32_e32 v84, 4, v86
	v_mov_b32_e32 v85, 0
	s_waitcnt lgkmcnt(0)
	s_lshl_b32 s3, s3, 3
	s_add_u32 s14, s12, 0xeb00000
	s_addc_u32 s15, s13, 0
	s_ashr_i32 s7, s6, 31
	s_lshl_b64 s[8:9], s[6:7], 13
	s_add_u32 s8, s14, s8
	s_addc_u32 s9, s15, s9
	v_lshl_add_u64 v[30:31], s[8:9], 0, v[84:85]
	s_movk_i32 s7, 0x1000
	flat_load_dwordx4 v[2:5], v[30:31] nt
	flat_load_dwordx4 v[90:93], v[30:31] offset:1024 nt
	flat_load_dwordx4 v[6:9], v[30:31] offset:2048 nt
	v_add_co_u32_e32 v32, vcc, s7, v30
	v_mbcnt_lo_u32_b32 v62, -1, 0
	s_nop 0
	v_addc_co_u32_e32 v33, vcc, 0, v31, vcc
	flat_load_dwordx4 v[10:13], v[32:33] nt
	flat_load_dwordx4 v[14:17], v[32:33] offset:1024 nt
	flat_load_dwordx4 v[18:21], v[32:33] offset:3072 nt
	flat_load_dwordx4 v[22:25], v[32:33] offset:2048 nt
	flat_load_dwordx4 v[26:29], v[30:31] offset:3072 nt
	v_mbcnt_hi_u32_b32 v62, -1, v62
	v_and_b32_e32 v63, 64, v62
	v_xor_b32_e32 v64, 1, v62
	v_add_u32_e32 v63, 64, v63
	v_xor_b32_e32 v65, 2, v62
	v_cmp_lt_i32_e32 vcc, v64, v63
	v_xor_b32_e32 v66, 4, v62
	s_load_dwordx4 s[8:11], s[16:17], 0x58
	v_cndmask_b32_e32 v64, v62, v64, vcc
	v_cmp_lt_i32_e32 vcc, v65, v63
	v_xor_b32_e32 v67, 8, v62
	v_xor_b32_e32 v70, 16, v62
	v_cndmask_b32_e32 v65, v62, v65, vcc
	v_cmp_lt_i32_e32 vcc, v66, v63
	v_xor_b32_e32 v71, 32, v62
	v_or_b32_e32 v68, 0x1000, v84
	v_cndmask_b32_e32 v66, v62, v66, vcc
	v_cmp_lt_i32_e32 vcc, v67, v63
	v_or_b32_e32 v72, 0x1400, v84
	v_or_b32_e32 v76, 0x1800, v84
	v_cndmask_b32_e32 v67, v62, v67, vcc
	v_cmp_lt_i32_e32 vcc, v70, v63
	v_lshlrev_b32_e32 v98, 2, v64
	v_lshlrev_b32_e32 v99, 2, v65
	v_cndmask_b32_e32 v70, v62, v70, vcc
	v_cmp_lt_i32_e32 vcc, v71, v63
	s_waitcnt lgkmcnt(0)
	v_lshl_add_u64 v[64:65], s[10:11], 0, v[84:85]
	v_lshl_add_u64 v[78:79], s[14:15], 0, v[84:85]
	v_cndmask_b32_e32 v62, v62, v71, vcc
	v_lshlrev_b32_e32 v103, 2, v62
	v_lshl_add_u64 v[62:63], s[8:9], 0, v[84:85]
	v_or_b32_e32 v84, 0x1c00, v84
	v_lshl_add_u64 v[80:81], s[8:9], 0, v[84:85]
	v_lshl_add_u64 v[82:83], s[10:11], 0, v[84:85]
	v_lshlrev_b32_e32 v84, 3, v86
	s_mov_b64 s[18:19], 0x6900000
	v_mov_b32_e32 v69, v85
	v_mov_b32_e32 v73, v85
	v_mov_b32_e32 v77, v85
	v_lshl_add_u64 v[84:85], s[12:13], 0, v[84:85]
	v_mov_b32_e32 v1, 0x3727c5ac
	s_mov_b32 s16, 0x800000
	v_lshlrev_b32_e32 v100, 2, v66
	v_lshlrev_b32_e32 v101, 2, v67
	v_lshlrev_b32_e32 v102, 2, v70
	v_lshl_add_u64 v[66:67], s[8:9], 0, v[68:69]
	v_lshl_add_u64 v[68:69], s[10:11], 0, v[68:69]
	v_lshl_add_u64 v[70:71], s[8:9], 0, v[72:73]
	v_lshl_add_u64 v[72:73], s[10:11], 0, v[72:73]
	v_lshl_add_u64 v[74:75], s[8:9], 0, v[76:77]
	v_lshl_add_u64 v[76:77], s[10:11], 0, v[76:77]
	v_lshl_add_u64 v[84:85], v[84:85], 0, s[18:19]
	s_waitcnt vmcnt(0)
	v_mov_b32_e32 v87, v2
	v_mov_b32_e32 v89, v4
	v_mov_b32_e32 v86, v90
	v_mov_b32_e32 v2, v91
	v_mov_b32_e32 v88, v92
	v_mov_b32_e32 v4, v93
	v_mov_b32_e32 v90, v7
	v_mov_b32_e32 v91, v8
	v_mov_b32_e32 v7, v9
	v_mov_b32_e32 v8, v11
	v_mov_b32_e32 v92, v13
	v_mov_b32_e32 v94, v15
	v_mov_b32_e32 v95, v16
	v_mov_b32_e32 v15, v17
	v_mov_b32_e32 v16, v19
	v_mov_b32_e32 v96, v21
	s_branch .LBB0_1199

; __device__ __forceinline__ void ln_apply(f32x4 (&v)[8], const float* __restrict__ g, const float* __restrict__ b, bf16_t* hb, float* fo, int lane) {
;     float s = 0.f;
; #pragma unroll
;     for (int j = 0; j < 8; ++j) s += (v[j][0] + v[j][1]) + (v[j][2] + v[j][3]);
;     const float mean = wave_sum(s) * (1.f / DM); float q = 0.f;
; #pragma unroll
;     for (int j = 0; j < 8; ++j) { v[j] = v[j] - mean; q += (v[j][0] * v[j][0] + v[j][1] * v[j][1]) + (v[j][2] * v[j][2] + v[j][3] * v[j][3]); }
;     const float rstd = rsqrtf(wave_sum(q) * (1.f / DM) + LN_EPS);
.LBB0_1199:
	s_add_i32 s8, s6, s3
	s_cmpk_gt_i32 s8, 0x400f
	s_cbranch_scc1 .LBB0_1201
	s_ashr_i32 s9, s8, 31
	s_lshl_b64 s[10:11], s[8:9], 13
	v_lshl_add_u64 v[46:47], v[78:79], 0, s[10:11]
	v_add_co_u32_e32 v104, vcc, 0x1000, v46
	flat_load_dwordx4 v[42:45], v[46:47] nt
	flat_load_dwordx4 v[38:41], v[46:47] offset:1024 nt
	flat_load_dwordx4 v[34:37], v[46:47] offset:2048 nt
	flat_load_dwordx4 v[30:33], v[46:47] offset:3072 nt
	v_addc_co_u32_e32 v105, vcc, 0, v47, vcc
	flat_load_dwordx4 v[58:61], v[104:105] nt
	flat_load_dwordx4 v[54:57], v[104:105] offset:1024 nt
	flat_load_dwordx4 v[50:53], v[104:105] offset:2048 nt
	flat_load_dwordx4 v[46:49], v[104:105] offset:3072 nt
.LBB0_1201:
	v_pk_add_f32 v[104:105], v[86:87], v[2:3]
	v_pk_add_f32 v[106:107], v[88:89], v[4:5]
	v_add_f32_e32 v11, v26, v27
	v_pk_add_f32 v[104:105], v[104:105], v[106:107]
	v_add_f32_e32 v19, v22, v23
	v_add_f32_e32 v9, 0, v105
	v_add_f32_e32 v93, v104, v9
	v_pk_add_f32 v[104:105], v[90:91], v[6:7]
	v_add_f32_e32 v9, v28, v29
	v_pk_add_f32 v[104:105], v[104:105], v[104:105] op_sel_hi:[0,1]
	v_mov_b32_e32 v13, v105
	v_pk_add_f32 v[106:107], v[10:11], v[8:9]
	v_pk_add_f32 v[104:105], v[12:13], v[92:93]
	v_add_f32_e32 v17, v24, v25
	v_pk_add_f32 v[104:105], v[106:107], v[104:105]
	v_pk_add_f32 v[106:107], v[94:95], v[14:15]
	v_pk_add_f32 v[104:105], v[104:105], v[104:105] op_sel_hi:[0,1]
	v_pk_add_f32 v[106:107], v[106:107], v[106:107] op_sel_hi:[0,1]
	v_mov_b32_e32 v21, v107
	v_mov_b32_e32 v97, v105
	v_pk_add_f32 v[108:109], v[18:19], v[16:17]
	v_pk_add_f32 v[104:105], v[20:21], v[96:97]
	s_ashr_i32 s7, s6, 31
	v_pk_add_f32 v[104:105], v[108:109], v[104:105]
	s_lshl_b64 s[10:11], s[6:7], 12
	v_add_f32_e32 v9, v104, v105
	ds_bpermute_b32 v11, v98, v9
	s_cmpk_gt_i32 s8, 0x400f
	s_waitcnt lgkmcnt(0)
	v_add_f32_e32 v9, v9, v11
	ds_bpermute_b32 v11, v99, v9
	s_waitcnt lgkmcnt(0)
	v_add_f32_e32 v9, v9, v11
	ds_bpermute_b32 v11, v100, v9
	s_waitcnt lgkmcnt(0)
	v_add_f32_e32 v9, v9, v11
	ds_bpermute_b32 v11, v101, v9
	s_waitcnt lgkmcnt(0)
	v_add_f32_e32 v9, v9, v11
	ds_bpermute_b32 v11, v102, v9
	s_waitcnt lgkmcnt(0)
	v_add_f32_e32 v9, v9, v11
	ds_bpermute_b32 v11, v103, v9
	s_waitcnt lgkmcnt(0)
	v_add_f32_e32 v9, v9, v11
	v_fmac_f32_e32 v3, 0xba000000, v9
	v_fmac_f32_e32 v2, 0xba000000, v9
	v_fmac_f32_e32 v87, 0xba000000, v9
	v_fmac_f32_e32 v86, 0xba000000, v9
	v_mov_b32_e32 v106, v3
	v_mov_b32_e32 v107, v2
	v_fmac_f32_e32 v5, 0xba000000, v9
	v_fmac_f32_e32 v4, 0xba000000, v9
	v_mov_b32_e32 v104, v87
	v_mov_b32_e32 v105, v86
	v_pk_mul_f32 v[106:107], v[106:107], v[106:107]
	v_fmac_f32_e32 v89, 0xba000000, v9
	v_fmac_f32_e32 v88, 0xba000000, v9
	v_pk_fma_f32 v[104:105], v[104:105], v[104:105], v[106:107]
	v_mov_b32_e32 v106, v5
	v_mov_b32_e32 v107, v4
	v_mov_b32_e32 v108, v89
	v_mov_b32_e32 v109, v88
	v_pk_mul_f32 v[106:107], v[106:107], v[106:107]
	v_fmac_f32_e32 v7, 0xba000000, v9
	v_pk_fma_f32 v[106:107], v[108:109], v[108:109], v[106:107]
	v_fmac_f32_e32 v91, 0xba000000, v9
	v_fmac_f32_e32 v90, 0xba000000, v9
	v_fmac_f32_e32 v6, 0xba000000, v9
	v_pk_add_f32 v[104:105], v[104:105], v[106:107]
	v_mov_b32_e32 v112, v91
	v_mov_b32_e32 v113, v7
	v_mov_b32_e32 v114, v6
	v_mov_b32_e32 v115, v90
	v_pk_add_f32 v[104:105], v[104:105], v[104:105] op_sel_hi:[0,1]
	v_pk_mul_f32 v[106:107], v[112:113], v[112:113]
	v_pk_mul_f32 v[108:109], v[114:115], v[114:115]
	v_fmac_f32_e32 v26, 0xba000000, v9
	v_pk_mov_b32 v[110:111], v[108:109], v[106:107] op_sel:[1,0]
	v_mov_b32_e32 v109, v107
	v_fmac_f32_e32 v28, 0xba000000, v9
	v_fmac_f32_e32 v27, 0xba000000, v9
	v_mul_f32_e32 v104, v26, v26
	v_pk_add_f32 v[106:107], v[110:111], v[108:109]
	v_fmac_f32_e32 v29, 0xba000000, v9
	v_pk_fma_f32 v[108:109], v[26:27], v[26:27], v[104:105] op_sel_hi:[1,1,0]
	v_mul_f32_e32 v104, v28, v28
	v_pk_add_f32 v[106:107], v[106:107], v[106:107] op_sel_hi:[0,1]
	v_pk_fma_f32 v[110:111], v[28:29], v[28:29], v[104:105] op_sel_hi:[1,1,0]
	v_fmac_f32_e32 v92, 0xba000000, v9
	v_fmac_f32_e32 v12, 0xba000000, v9
	v_fmac_f32_e32 v8, 0xba000000, v9
	v_fmac_f32_e32 v10, 0xba000000, v9
	v_mul_f32_e32 v108, v10, v10
	v_mul_f32_e32 v110, v8, v8
	v_mul_f32_e32 v106, v12, v12
	v_mul_f32_e32 v104, v92, v92
	v_pk_add_f32 v[108:109], v[108:109], v[110:111]
	v_pk_add_f32 v[104:105], v[106:107], v[104:105]
	v_fmac_f32_e32 v15, 0xba000000, v9
	v_pk_add_f32 v[104:105], v[108:109], v[104:105]
	v_fmac_f32_e32 v95, 0xba000000, v9
	v_pk_add_f32 v[116:117], v[104:105], v[104:105] op_sel_hi:[0,1]
	flat_load_dwordx4 v[104:107], v[62:63]
	flat_load_dwordx4 v[108:111], v[64:65]
	v_fmac_f32_e32 v94, 0xba000000, v9
	v_fmac_f32_e32 v14, 0xba000000, v9
	v_mov_b32_e32 v118, v95
	v_mov_b32_e32 v119, v15
	v_mov_b32_e32 v122, v14
	v_mov_b32_e32 v123, v94
	v_pk_mul_f32 v[120:121], v[118:119], v[118:119]
	v_pk_mul_f32 v[124:125], v[122:123], v[122:123]
	v_fmac_f32_e32 v22, 0xba000000, v9
	v_pk_mov_b32 v[126:127], v[124:125], v[120:121] op_sel:[1,0]
	v_mov_b32_e32 v125, v121
	v_fmac_f32_e32 v24, 0xba000000, v9
	v_fmac_f32_e32 v23, 0xba000000, v9
	v_mul_f32_e32 v116, v22, v22
	v_pk_add_f32 v[120:121], v[126:127], v[124:125]
	v_fmac_f32_e32 v25, 0xba000000, v9
	v_pk_fma_f32 v[124:125], v[22:23], v[22:23], v[116:117] op_sel_hi:[1,1,0]
	v_mul_f32_e32 v116, v24, v24
	v_pk_add_f32 v[120:121], v[120:121], v[120:121] op_sel_hi:[0,1]
	v_pk_fma_f32 v[126:127], v[24:25], v[24:25], v[116:117] op_sel_hi:[1,1,0]
	v_fmac_f32_e32 v96, 0xba000000, v9
	v_fmac_f32_e32 v20, 0xba000000, v9
	v_fmac_f32_e32 v16, 0xba000000, v9
	v_fmac_f32_e32 v18, 0xba000000, v9
	v_mul_f32_e32 v124, v18, v18
	v_mul_f32_e32 v126, v16, v16
	v_mul_f32_e32 v120, v20, v20
	v_mul_f32_e32 v116, v96, v96
	v_pk_add_f32 v[124:125], v[124:125], v[126:127]
	v_pk_add_f32 v[116:117], v[120:121], v[116:117]
	v_mov_b32_e32 v120, v89
	v_pk_add_f32 v[116:117], v[124:125], v[116:117]
	v_mov_b32_e32 v121, v5
	v_add_f32_e32 v9, v116, v117
	ds_bpermute_b32 v11, v98, v9
	v_mov_b32_e32 v116, v87
	v_mov_b32_e32 v117, v3
	v_mov_b32_e32 v126, v86
	v_mov_b32_e32 v127, v2
	s_waitcnt lgkmcnt(0)
; __device__ __forceinline__ unsigned cvt_pk_bf16(float lo, float hi) { unsigned r; asm volatile("v_cvt_pk_bf16_f32 %0, %1, %2" : "=v"(r) : "v"(lo), "v"(hi)); return r; }
; __device__ __forceinline__ void ln_apply(f32x4 (&v)[8], const float* __restrict__ g, const float* __restrict__ b, bf16_t* hb, float* fo, int lane) {
;     ...
;     const float rstd = rsqrtf(wave_sum(q) * (1.f / DM) + LN_EPS);
; #pragma unroll
;     for (int j = 0; j < 8; ++j) { const int c = (lane + 64 * j) * 4; const f32x4 gg = *(const f32x4*)(g + c), bb = *(const f32x4*)(b + c);
;         const f32x4 y = v[j] * rstd * gg + bb;
;         if (hb) { u32x2 w; w.x = cvt_pk_bf16(y[0], y[1]); w.y = cvt_pk_bf16(y[2], y[3]); *(u32x2*)(hb + c) = w; }
;         if (fo) *(f32x4*)(fo + c) = y; }
	v_add_f32_e32 v9, v9, v11
	ds_bpermute_b32 v11, v99, v9
	v_mov_b32_e32 v128, v88
	v_mov_b32_e32 v129, v4
	v_mov_b32_e32 v13, v92
	v_mov_b32_e32 v19, v16
	s_waitcnt lgkmcnt(0)
	v_add_f32_e32 v9, v9, v11
	ds_bpermute_b32 v11, v100, v9
	v_mov_b32_e32 v21, v96
	s_waitcnt lgkmcnt(0)
	v_add_f32_e32 v9, v9, v11
	ds_bpermute_b32 v11, v101, v9
	s_waitcnt lgkmcnt(0)
	v_add_f32_e32 v9, v9, v11
	ds_bpermute_b32 v11, v102, v9
	s_waitcnt lgkmcnt(0)
	v_add_f32_e32 v9, v9, v11
	ds_bpermute_b32 v11, v103, v9
	s_waitcnt lgkmcnt(0)
	v_add_f32_e32 v9, v9, v11
	v_fmamk_f32 v9, v9, 0x3a000000, v1
	v_mul_f32_e32 v11, 0x4b800000, v9
	v_cmp_gt_f32_e32 vcc, s16, v9
	s_nop 1
	v_cndmask_b32_e32 v9, v9, v11, vcc
	v_rsq_f32_e32 v9, v9
	s_nop 0
	v_mul_f32_e32 v11, 0x45800000, v9
	v_cndmask_b32_e32 v124, v9, v11, vcc
	v_pk_mul_f32 v[116:117], v[116:117], v[124:125] op_sel_hi:[1,0]
	v_pk_mul_f32 v[120:121], v[120:121], v[124:125] op_sel_hi:[1,0]
	s_waitcnt vmcnt(0)
	v_pk_fma_f32 v[104:105], v[104:105], v[116:117], v[108:109]
	v_pk_fma_f32 v[106:107], v[106:107], v[120:121], v[110:111]
	v_cvt_pk_bf16_f32 v116, v104, v105
	v_pk_mul_f32 v[126:127], v[126:127], v[124:125] op_sel_hi:[1,0]
	v_cvt_pk_bf16_f32 v117, v106, v107
	flat_load_dwordx4 v[104:107], v[62:63] offset:1024
	flat_load_dwordx4 v[108:111], v[64:65] offset:1024
	v_pk_mul_f32 v[128:129], v[128:129], v[124:125] op_sel_hi:[1,0]
	v_lshl_add_u64 v[120:121], v[84:85], 0, s[10:11]
	flat_store_dwordx2 v[120:121], v[116:117]
	v_pk_mul_f32 v[114:115], v[114:115], v[124:125] op_sel_hi:[1,0]
	v_pk_mul_f32 v[112:113], v[112:113], v[124:125] op_sel_hi:[1,0]
	v_mov_b32_e32 v11, v8
	s_mov_b64 s[10:11], -1
	s_waitcnt vmcnt(0) lgkmcnt(0)
	v_pk_fma_f32 v[106:107], v[106:107], v[128:129], v[110:111]
	v_pk_fma_f32 v[104:105], v[104:105], v[126:127], v[108:109]
	s_nop 0
	v_cvt_pk_bf16_f32 v116, v104, v105
	v_cvt_pk_bf16_f32 v117, v106, v107
	flat_load_dwordx4 v[104:107], v[62:63] offset:2048
	flat_load_dwordx4 v[108:111], v[64:65] offset:2048
	s_waitcnt vmcnt(0) lgkmcnt(0)
	v_pk_fma_f32 v[106:107], v[106:107], v[112:113], v[110:111]
	v_pk_fma_f32 v[104:105], v[104:105], v[114:115], v[108:109]
	flat_store_dwordx2 v[120:121], v[116:117] offset:512
	v_cvt_pk_bf16_f32 v112, v104, v105
	v_cvt_pk_bf16_f32 v113, v106, v107
	flat_load_dwordx4 v[104:107], v[62:63] offset:3072
	flat_load_dwordx4 v[108:111], v[64:65] offset:3072
	v_pk_mul_f32 v[114:115], v[26:27], v[124:125] op_sel_hi:[1,0]
	v_pk_mul_f32 v[116:117], v[28:29], v[124:125] op_sel_hi:[1,0]
	flat_store_dwordx2 v[120:121], v[112:113] offset:1024
	s_waitcnt vmcnt(0) lgkmcnt(0)
	v_pk_fma_f32 v[106:107], v[106:107], v[116:117], v[110:111]
	v_pk_fma_f32 v[104:105], v[104:105], v[114:115], v[108:109]
	v_pk_mul_f32 v[114:115], v[10:11], v[124:125] op_sel_hi:[1,0]
	v_cvt_pk_bf16_f32 v112, v104, v105
	v_cvt_pk_bf16_f32 v113, v106, v107
	flat_load_dwordx4 v[104:107], v[66:67]
	flat_load_dwordx4 v[108:111], v[68:69]
	v_pk_mul_f32 v[116:117], v[12:13], v[124:125] op_sel_hi:[1,0]
	flat_store_dwordx2 v[120:121], v[112:113] offset:1536
	s_waitcnt vmcnt(0) lgkmcnt(0)
	v_pk_fma_f32 v[106:107], v[106:107], v[116:117], v[110:111]
	v_pk_fma_f32 v[104:105], v[104:105], v[114:115], v[108:109]
	v_pk_mul_f32 v[114:115], v[122:123], v[124:125] op_sel_hi:[1,0]
	v_cvt_pk_bf16_f32 v112, v104, v105
	v_cvt_pk_bf16_f32 v113, v106, v107
	flat_load_dwordx4 v[104:107], v[70:71]
	flat_load_dwordx4 v[108:111], v[72:73]
	v_pk_mul_f32 v[116:117], v[118:119], v[124:125] op_sel_hi:[1,0]
	flat_store_dwordx2 v[120:121], v[112:113] offset:2048
	s_waitcnt vmcnt(0) lgkmcnt(0)
	v_pk_fma_f32 v[106:107], v[106:107], v[116:117], v[110:111]
	v_pk_fma_f32 v[104:105], v[104:105], v[114:115], v[108:109]
	v_pk_mul_f32 v[114:115], v[22:23], v[124:125] op_sel_hi:[1,0]
	v_cvt_pk_bf16_f32 v112, v104, v105
	v_cvt_pk_bf16_f32 v113, v106, v107
	flat_load_dwordx4 v[104:107], v[74:75]
	flat_load_dwordx4 v[108:111], v[76:77]
	v_pk_mul_f32 v[116:117], v[24:25], v[124:125] op_sel_hi:[1,0]
	flat_store_dwordx2 v[120:121], v[112:113] offset:2560
	s_waitcnt vmcnt(0) lgkmcnt(0)
	v_pk_fma_f32 v[106:107], v[116:117], v[106:107], v[110:111]
	v_pk_fma_f32 v[104:105], v[114:115], v[104:105], v[108:109]
	v_pk_mul_f32 v[114:115], v[18:19], v[124:125] op_sel_hi:[1,0]
	v_cvt_pk_bf16_f32 v112, v104, v105
	v_cvt_pk_bf16_f32 v113, v106, v107
	flat_load_dwordx4 v[104:107], v[80:81]
	flat_load_dwordx4 v[108:111], v[82:83]
	v_pk_mul_f32 v[116:117], v[20:21], v[124:125] op_sel_hi:[1,0]
	flat_store_dwordx2 v[120:121], v[112:113] offset:3072
	s_waitcnt vmcnt(0) lgkmcnt(0)
	v_pk_fma_f32 v[104:105], v[114:115], v[104:105], v[108:109]
	v_pk_fma_f32 v[106:107], v[116:117], v[106:107], v[110:111]
	v_cvt_pk_bf16_f32 v104, v104, v105
	s_nop 0
	v_cvt_pk_bf16_f32 v105, v106, v107
	flat_store_dwordx2 v[120:121], v[104:105] offset:3584
	s_cbranch_scc1 .LBB0_1198
	s_add_i32 s12, s8, s3
	s_cmpk_gt_i32 s12, 0x400f
	s_cselect_b64 s[10:11], -1, 0
	s_and_b64 vcc, exec, s[10:11]
	s_cbranch_vccnz .LBB0_1197
	s_ashr_i32 s13, s12, 31
	s_lshl_b64 s[6:7], s[12:13], 13
	v_lshl_add_u64 v[86:87], v[78:79], 0, s[6:7]
	flat_load_dwordx4 v[2:5], v[86:87] nt
	flat_load_dwordx4 v[90:93], v[86:87] offset:1024 nt
	flat_load_dwordx4 v[6:9], v[86:87] offset:2048 nt
	v_add_co_u32_e32 v88, vcc, 0x1000, v86
	s_mov_b32 s6, s12
	s_nop 0
	v_addc_co_u32_e32 v89, vcc, 0, v87, vcc
	flat_load_dwordx4 v[10:13], v[88:89] nt
	flat_load_dwordx4 v[14:17], v[88:89] offset:1024 nt
	flat_load_dwordx4 v[18:21], v[88:89] offset:3072 nt
	flat_load_dwordx4 v[22:25], v[88:89] offset:2048 nt
	flat_load_dwordx4 v[26:29], v[86:87] offset:3072 nt
	s_waitcnt vmcnt(0) lgkmcnt(0)
	v_mov_b32_e32 v87, v2
	v_mov_b32_e32 v89, v4
	v_mov_b32_e32 v86, v90
	v_mov_b32_e32 v2, v91
	v_mov_b32_e32 v88, v92
	v_mov_b32_e32 v4, v93
	v_mov_b32_e32 v90, v7
	v_mov_b32_e32 v91, v8
	v_mov_b32_e32 v7, v9
	v_mov_b32_e32 v8, v11
	v_mov_b32_e32 v92, v13
	v_mov_b32_e32 v94, v15
	v_mov_b32_e32 v95, v16
	v_mov_b32_e32 v15, v17
	v_mov_b32_e32 v16, v19
	v_mov_b32_e32 v96, v21
	s_branch .LBB0_1197

; #define PH_BEGIN const Params P = load_params(); unsigned char* ws = P.ws;
; __device__ __forceinline__ void ln_load(f32x4 (&v)[8], const float* z, int lane) {
; #pragma unroll
;     for (int j = 0; j < 8; ++j) v[j] = ((const f32x4*)z)[lane + 64 * j];
; }
; template <int L, int K>
; __device__ __forceinline__ void phase_body(char* lds, int rep_) {
;     ...
;     if constexpr (K == 8) { PH_BEGIN
;         const float* g2 = P.in[15] + L * DM; const float* b2 = P.in[16] + L * DM; const float* ZS = (const float*)(ws + WS_ZS); bf16_t* HB = (bf16_t*)(ws + WS_HB);
;         if (L == 0) {
;             const float* lg_ = g2; const float* lb_ = b2;
;     ...
;             LN_ROWS(gw, LTOK, NGW, ZR_, HR_, FR_);
.LBB0_1448:
	s_cmp_lt_i32 s80, 10
	s_cselect_b64 s[6:7], -1, 0
	s_cmp_gt_i32 s81, 9
	s_cselect_b64 s[8:9], -1, 0
	s_and_b64 s[6:7], s[6:7], s[8:9]
	s_andn2_b64 vcc, exec, s[6:7]
	s_cbranch_vccnz .LBB0_1546
	v_mov_b32_e32 v1, v194
	s_mov_b64 s[18:19], s[0:1]
	v_readfirstlane_b32 s3, v1
	s_ashr_i32 s22, s3, 6
	s_load_dword s3, s[0:1], 0xa0
	s_load_dwordx2 s[16:17], s[18:19], 0x10
	s_load_dwordx2 s[6:7], s[18:19], 0x50
	s_load_dwordx4 s[8:11], s[18:19], 0x88
	s_lshl_b32 s12, s2, 3
	v_and_b32_e32 v62, 63, v1
	s_add_i32 s20, s22, s12
	s_waitcnt lgkmcnt(0)
	s_lshl_b32 s21, s3, 3
	s_cmpk_gt_i32 s20, 0x400f
	v_lshlrev_b32_e32 v64, 3, v62
	s_cbranch_scc1 .LBB0_1458
	s_add_u32 s23, s10, 0x20000
	s_addc_u32 s24, s11, 0
	s_ashr_i32 s12, s20, 31
	s_add_i32 s14, s20, -16
	s_cmp_gt_i32 s20, 15
	s_cselect_b32 s13, 0, s12
	s_cselect_b32 s12, s14, s20
	s_cselect_b32 s14, s9, s24
	s_cselect_b32 s15, s8, s23
	s_lshl_b64 s[12:13], s[12:13], 13
	s_add_u32 s12, s15, s12
	s_addc_u32 s13, s14, s13
	v_mov_b32_e32 v67, 0
	v_lshlrev_b32_e32 v66, 4, v62
	v_lshl_add_u64 v[30:31], s[12:13], 0, v[66:67]
	s_movk_i32 s25, 0x1000
	flat_load_dwordx4 v[2:5], v[30:31] nt
	flat_load_dwordx4 v[94:97], v[30:31] offset:1024 nt
	flat_load_dwordx4 v[6:9], v[30:31] offset:2048 nt
	v_add_co_u32_e32 v32, vcc, s25, v30
	v_mbcnt_lo_u32_b32 v65, -1, 0
	s_nop 0
	v_addc_co_u32_e32 v33, vcc, 0, v31, vcc
	flat_load_dwordx4 v[10:13], v[32:33] nt
	flat_load_dwordx4 v[14:17], v[32:33] offset:1024 nt
	flat_load_dwordx4 v[18:21], v[32:33] offset:3072 nt
	flat_load_dwordx4 v[22:25], v[32:33] offset:2048 nt
	flat_load_dwordx4 v[26:29], v[30:31] offset:3072 nt
	v_mbcnt_hi_u32_b32 v70, -1, v65
	v_mov_b32_e32 v65, v67
	v_and_b32_e32 v71, 64, v70
	v_xor_b32_e32 v72, 1, v70
	v_lshl_add_u64 v[68:69], s[10:11], 0, v[64:65]
	v_add_u32_e32 v65, 64, v71
	v_xor_b32_e32 v73, 2, v70
	v_cmp_lt_i32_e32 vcc, v72, v65
	v_xor_b32_e32 v74, 4, v70
	s_load_dwordx4 s[12:15], s[18:19], 0x78
	v_cndmask_b32_e32 v71, v70, v72, vcc
	v_cmp_lt_i32_e32 vcc, v73, v65
	v_xor_b32_e32 v75, 8, v70
	v_xor_b32_e32 v78, 16, v70
	v_cndmask_b32_e32 v72, v70, v73, vcc
	v_cmp_lt_i32_e32 vcc, v74, v65
	v_xor_b32_e32 v79, 32, v70
	s_mov_b64 s[28:29], 0x6900000
	v_cndmask_b32_e32 v73, v70, v74, vcc
	v_cmp_lt_i32_e32 vcc, v75, v65
	v_or_b32_e32 v76, 0x1000, v66
	v_mov_b32_e32 v77, v67
	v_cndmask_b32_e32 v74, v70, v75, vcc
	v_cmp_lt_i32_e32 vcc, v78, v65
	v_or_b32_e32 v80, 0x1400, v66
	v_mov_b32_e32 v81, v67
	v_cndmask_b32_e32 v75, v70, v78, vcc
	v_cmp_lt_i32_e32 vcc, v79, v65
	v_or_b32_e32 v84, 0x1800, v66
	v_mov_b32_e32 v85, v67
	v_cndmask_b32_e32 v70, v70, v79, vcc
	v_lshlrev_b32_e32 v65, 2, v71
	v_lshlrev_b32_e32 v102, 2, v72
	v_lshlrev_b32_e32 v103, 2, v73
	v_lshlrev_b32_e32 v106, 2, v70
	s_waitcnt lgkmcnt(0)
	v_lshl_add_u64 v[70:71], s[12:13], 0, v[66:67]
	v_lshl_add_u64 v[72:73], s[14:15], 0, v[66:67]
	v_or_b32_e32 v66, 0x1c00, v66
	v_mov_b32_e32 v63, 0x3727c5ac
	s_mov_b32 s26, 0x800000
	s_mov_b32 s18, s20
	v_lshl_add_u64 v[68:69], v[68:69], 0, s[28:29]
	v_lshlrev_b32_e32 v104, 2, v74
	v_lshlrev_b32_e32 v105, 2, v75
	v_lshl_add_u64 v[74:75], s[12:13], 0, v[76:77]
	v_lshl_add_u64 v[76:77], s[14:15], 0, v[76:77]
	v_lshl_add_u64 v[78:79], s[12:13], 0, v[80:81]
	v_lshl_add_u64 v[80:81], s[14:15], 0, v[80:81]
	v_lshl_add_u64 v[82:83], s[12:13], 0, v[84:85]
	v_lshl_add_u64 v[84:85], s[14:15], 0, v[84:85]
	v_lshl_add_u64 v[86:87], s[12:13], 0, v[66:67]
	v_lshl_add_u64 v[88:89], s[14:15], 0, v[66:67]
	s_waitcnt vmcnt(0)
	v_mov_b32_e32 v91, v2
	v_mov_b32_e32 v93, v4
	v_mov_b32_e32 v90, v94
	v_mov_b32_e32 v2, v95
	v_mov_b32_e32 v92, v96
	v_mov_b32_e32 v4, v97
	v_mov_b32_e32 v94, v7
	v_mov_b32_e32 v95, v8
	v_mov_b32_e32 v7, v9
	v_mov_b32_e32 v8, v11
	v_mov_b32_e32 v96, v13
	v_mov_b32_e32 v98, v15
	v_mov_b32_e32 v99, v16
	v_mov_b32_e32 v15, v17
	v_mov_b32_e32 v16, v19
	v_mov_b32_e32 v100, v21
	s_branch .LBB0_1453

; __device__ __forceinline__ void ln_apply(f32x4 (&v)[8], const float* __restrict__ g, const float* __restrict__ b, bf16_t* hb, float* fo, int lane) {
;     float s = 0.f;
; #pragma unroll
;     for (int j = 0; j < 8; ++j) s += (v[j][0] + v[j][1]) + (v[j][2] + v[j][3]);
;     const float mean = wave_sum(s) * (1.f / DM); float q = 0.f;
; #pragma unroll
;     for (int j = 0; j < 8; ++j) { v[j] = v[j] - mean; q += (v[j][0] * v[j][0] + v[j][1] * v[j][1]) + (v[j][2] * v[j][2] + v[j][3] * v[j][3]); }
;     const float rstd = rsqrtf(wave_sum(q) * (1.f / DM) + LN_EPS);
.LBB0_1453:
	s_add_i32 s12, s18, s21
	s_cmpk_gt_i32 s12, 0x400f
	s_cbranch_scc1 .LBB0_1455
	s_ashr_i32 s13, s12, 31
	s_add_i32 s14, s12, -16
	s_cmp_gt_i32 s12, 15
	s_cselect_b32 s15, 0, s13
	s_cselect_b32 s14, s14, s12
	s_cselect_b32 s13, s9, s24
	s_cselect_b32 s19, s8, s23
	s_lshl_b64 s[14:15], s[14:15], 13
	s_add_u32 s14, s19, s14
	s_addc_u32 s15, s13, s15
	v_lshlrev_b32_e32 v66, 4, v62
	v_lshl_add_u64 v[46:47], s[14:15], 0, v[66:67]
	v_add_co_u32_e32 v108, vcc, 0x1000, v46
	flat_load_dwordx4 v[42:45], v[46:47] nt
	flat_load_dwordx4 v[38:41], v[46:47] offset:1024 nt
	flat_load_dwordx4 v[34:37], v[46:47] offset:2048 nt
	flat_load_dwordx4 v[30:33], v[46:47] offset:3072 nt
	v_addc_co_u32_e32 v109, vcc, 0, v47, vcc
	flat_load_dwordx4 v[58:61], v[108:109] nt
	flat_load_dwordx4 v[54:57], v[108:109] offset:1024 nt
	flat_load_dwordx4 v[50:53], v[108:109] offset:2048 nt
	flat_load_dwordx4 v[46:49], v[108:109] offset:3072 nt
.LBB0_1455:
	v_pk_add_f32 v[108:109], v[90:91], v[2:3]
	v_pk_add_f32 v[110:111], v[92:93], v[4:5]
	v_add_f32_e32 v11, v26, v27
	v_pk_add_f32 v[108:109], v[108:109], v[110:111]
	v_add_f32_e32 v19, v22, v23
	v_add_f32_e32 v9, 0, v109
	v_add_f32_e32 v97, v108, v9
	v_pk_add_f32 v[108:109], v[94:95], v[6:7]
	v_add_f32_e32 v9, v28, v29
	v_pk_add_f32 v[108:109], v[108:109], v[108:109] op_sel_hi:[0,1]
	v_mov_b32_e32 v13, v109
	v_pk_add_f32 v[110:111], v[10:11], v[8:9]
	v_pk_add_f32 v[108:109], v[12:13], v[96:97]
	v_add_f32_e32 v17, v24, v25
	v_pk_add_f32 v[108:109], v[110:111], v[108:109]
	v_pk_add_f32 v[110:111], v[98:99], v[14:15]
	v_pk_add_f32 v[108:109], v[108:109], v[108:109] op_sel_hi:[0,1]
	v_pk_add_f32 v[110:111], v[110:111], v[110:111] op_sel_hi:[0,1]
	v_mov_b32_e32 v21, v111
	v_mov_b32_e32 v101, v109
	v_pk_add_f32 v[112:113], v[18:19], v[16:17]
	v_pk_add_f32 v[108:109], v[20:21], v[100:101]
	s_ashr_i32 s19, s18, 31
	v_pk_add_f32 v[108:109], v[112:113], v[108:109]
	s_lshl_b64 s[14:15], s[18:19], 12
	v_add_f32_e32 v9, v108, v109
	ds_bpermute_b32 v11, v65, v9
	s_cmpk_gt_i32 s12, 0x400f
	s_waitcnt lgkmcnt(0)
	v_add_f32_e32 v9, v9, v11
	ds_bpermute_b32 v11, v102, v9
	s_waitcnt lgkmcnt(0)
	v_add_f32_e32 v9, v9, v11
	ds_bpermute_b32 v11, v103, v9
	s_waitcnt lgkmcnt(0)
	v_add_f32_e32 v9, v9, v11
	ds_bpermute_b32 v11, v104, v9
	s_waitcnt lgkmcnt(0)
	v_add_f32_e32 v9, v9, v11
	ds_bpermute_b32 v11, v105, v9
	s_waitcnt lgkmcnt(0)
	v_add_f32_e32 v9, v9, v11
	ds_bpermute_b32 v11, v106, v9
	s_waitcnt lgkmcnt(0)
	v_add_f32_e32 v9, v9, v11
	v_fmac_f32_e32 v3, 0xba000000, v9
	v_fmac_f32_e32 v2, 0xba000000, v9
	v_fmac_f32_e32 v91, 0xba000000, v9
	v_fmac_f32_e32 v90, 0xba000000, v9
	v_mov_b32_e32 v110, v3
	v_mov_b32_e32 v111, v2
	v_fmac_f32_e32 v5, 0xba000000, v9
	v_fmac_f32_e32 v4, 0xba000000, v9
	v_mov_b32_e32 v108, v91
	v_mov_b32_e32 v109, v90
	v_pk_mul_f32 v[110:111], v[110:111], v[110:111]
	v_fmac_f32_e32 v93, 0xba000000, v9
	v_fmac_f32_e32 v92, 0xba000000, v9
	v_pk_fma_f32 v[108:109], v[108:109], v[108:109], v[110:111]
	v_mov_b32_e32 v110, v5
	v_mov_b32_e32 v111, v4
	v_mov_b32_e32 v112, v93
	v_mov_b32_e32 v113, v92
	v_pk_mul_f32 v[110:111], v[110:111], v[110:111]
	v_fmac_f32_e32 v7, 0xba000000, v9
	v_fmac_f32_e32 v95, 0xba000000, v9
	v_fmac_f32_e32 v94, 0xba000000, v9
	v_fmac_f32_e32 v6, 0xba000000, v9
	v_pk_fma_f32 v[110:111], v[112:113], v[112:113], v[110:111]
	v_mov_b32_e32 v116, v95
	v_mov_b32_e32 v117, v7
	v_mov_b32_e32 v118, v6
	v_mov_b32_e32 v119, v94
	v_pk_add_f32 v[108:109], v[108:109], v[110:111]
	v_pk_mul_f32 v[110:111], v[116:117], v[116:117]
	v_pk_mul_f32 v[112:113], v[118:119], v[118:119]
	v_fmac_f32_e32 v26, 0xba000000, v9
	v_pk_mov_b32 v[114:115], v[112:113], v[110:111] op_sel:[1,0]
	v_mov_b32_e32 v113, v111
	v_fmac_f32_e32 v28, 0xba000000, v9
	v_fmac_f32_e32 v27, 0xba000000, v9
	v_mul_f32_e32 v66, v26, v26
	v_pk_add_f32 v[110:111], v[114:115], v[112:113]
	v_fmac_f32_e32 v29, 0xba000000, v9
	v_pk_fma_f32 v[112:113], v[26:27], v[26:27], v[66:67] op_sel_hi:[1,1,0]
	v_mul_f32_e32 v66, v28, v28
	v_pk_add_f32 v[108:109], v[108:109], v[108:109] op_sel_hi:[0,1]
	v_pk_add_f32 v[110:111], v[110:111], v[110:111] op_sel_hi:[0,1]
	v_pk_fma_f32 v[114:115], v[28:29], v[28:29], v[66:67] op_sel_hi:[1,1,0]
	v_fmac_f32_e32 v96, 0xba000000, v9
	v_fmac_f32_e32 v12, 0xba000000, v9
	v_fmac_f32_e32 v8, 0xba000000, v9
	v_fmac_f32_e32 v10, 0xba000000, v9
	v_mul_f32_e32 v112, v10, v10
	v_mul_f32_e32 v114, v8, v8
	v_mul_f32_e32 v110, v12, v12
	v_mul_f32_e32 v108, v96, v96
	v_pk_add_f32 v[112:113], v[112:113], v[114:115]
	v_pk_add_f32 v[108:109], v[110:111], v[108:109]
	v_fmac_f32_e32 v15, 0xba000000, v9
	v_pk_add_f32 v[108:109], v[112:113], v[108:109]
	v_fmac_f32_e32 v99, 0xba000000, v9
	v_pk_add_f32 v[120:121], v[108:109], v[108:109] op_sel_hi:[0,1]
	flat_load_dwordx4 v[108:111], v[70:71]
	flat_load_dwordx4 v[112:115], v[72:73]
	v_fmac_f32_e32 v98, 0xba000000, v9
	v_fmac_f32_e32 v14, 0xba000000, v9
	v_mov_b32_e32 v122, v99
	v_mov_b32_e32 v123, v15
	v_mov_b32_e32 v126, v14
	v_mov_b32_e32 v127, v98
	v_pk_mul_f32 v[124:125], v[122:123], v[122:123]
	v_pk_mul_f32 v[128:129], v[126:127], v[126:127]
	v_fmac_f32_e32 v22, 0xba000000, v9
	v_pk_mov_b32 v[130:131], v[128:129], v[124:125] op_sel:[1,0]
	v_mov_b32_e32 v129, v125
	v_fmac_f32_e32 v24, 0xba000000, v9
	v_fmac_f32_e32 v23, 0xba000000, v9
	v_mul_f32_e32 v66, v22, v22
	v_pk_add_f32 v[124:125], v[130:131], v[128:129]
	v_fmac_f32_e32 v25, 0xba000000, v9
	v_pk_fma_f32 v[128:129], v[22:23], v[22:23], v[66:67] op_sel_hi:[1,1,0]
	v_mul_f32_e32 v66, v24, v24
	v_pk_add_f32 v[124:125], v[124:125], v[124:125] op_sel_hi:[0,1]
	v_pk_fma_f32 v[130:131], v[24:25], v[24:25], v[66:67] op_sel_hi:[1,1,0]
	v_fmac_f32_e32 v100, 0xba000000, v9
	v_fmac_f32_e32 v20, 0xba000000, v9
	v_fmac_f32_e32 v16, 0xba000000, v9
	v_fmac_f32_e32 v18, 0xba000000, v9
	v_mul_f32_e32 v128, v18, v18
	v_mul_f32_e32 v130, v16, v16
	v_mul_f32_e32 v124, v20, v20
	v_mul_f32_e32 v120, v100, v100
	v_pk_add_f32 v[128:129], v[128:129], v[130:131]
	v_pk_add_f32 v[120:121], v[124:125], v[120:121]
	v_mov_b32_e32 v124, v93
	v_pk_add_f32 v[120:121], v[128:129], v[120:121]
	v_mov_b32_e32 v125, v5
	v_add_f32_e32 v9, v120, v121
	ds_bpermute_b32 v11, v65, v9
	v_mov_b32_e32 v120, v91
	v_mov_b32_e32 v121, v3
	v_mov_b32_e32 v128, v90
	v_mov_b32_e32 v129, v2
	s_waitcnt lgkmcnt(0)
; __device__ __forceinline__ unsigned cvt_pk_bf16(float lo, float hi) { unsigned r; asm volatile("v_cvt_pk_bf16_f32 %0, %1, %2" : "=v"(r) : "v"(lo), "v"(hi)); return r; }
; __device__ __forceinline__ void ln_apply(f32x4 (&v)[8], const float* __restrict__ g, const float* __restrict__ b, bf16_t* hb, float* fo, int lane) {
;     ...
;     const float rstd = rsqrtf(wave_sum(q) * (1.f / DM) + LN_EPS);
; #pragma unroll
;     for (int j = 0; j < 8; ++j) { const int c = (lane + 64 * j) * 4; const f32x4 gg = *(const f32x4*)(g + c), bb = *(const f32x4*)(b + c);
;         const f32x4 y = v[j] * rstd * gg + bb;
;         if (hb) { u32x2 w; w.x = cvt_pk_bf16(y[0], y[1]); w.y = cvt_pk_bf16(y[2], y[3]); *(u32x2*)(hb + c) = w; }
;         if (fo) *(f32x4*)(fo + c) = y; }
	v_add_f32_e32 v9, v9, v11
	ds_bpermute_b32 v11, v102, v9
	v_mov_b32_e32 v130, v92
	v_mov_b32_e32 v131, v4
	v_mov_b32_e32 v13, v96
	v_mov_b32_e32 v19, v16
	s_waitcnt lgkmcnt(0)
	v_add_f32_e32 v9, v9, v11
	ds_bpermute_b32 v11, v103, v9
	v_mov_b32_e32 v21, v100
	s_waitcnt lgkmcnt(0)
	v_add_f32_e32 v9, v9, v11
	ds_bpermute_b32 v11, v104, v9
	s_waitcnt lgkmcnt(0)
	v_add_f32_e32 v9, v9, v11
	ds_bpermute_b32 v11, v105, v9
	s_waitcnt lgkmcnt(0)
	v_add_f32_e32 v9, v9, v11
	ds_bpermute_b32 v11, v106, v9
	s_waitcnt lgkmcnt(0)
	v_add_f32_e32 v9, v9, v11
	v_fmamk_f32 v9, v9, 0x3a000000, v63
	v_mul_f32_e32 v11, 0x4b800000, v9
	v_cmp_gt_f32_e32 vcc, s26, v9
	s_nop 1
	v_cndmask_b32_e32 v9, v9, v11, vcc
	v_rsq_f32_e32 v9, v9
	s_nop 0
	v_mul_f32_e32 v11, 0x45800000, v9
	v_cndmask_b32_e32 v66, v9, v11, vcc
	v_pk_mul_f32 v[120:121], v[120:121], v[66:67] op_sel_hi:[1,0]
	v_pk_mul_f32 v[124:125], v[124:125], v[66:67] op_sel_hi:[1,0]
	s_waitcnt vmcnt(0)
	v_pk_fma_f32 v[108:109], v[108:109], v[120:121], v[112:113]
	v_pk_fma_f32 v[110:111], v[110:111], v[124:125], v[114:115]
	v_cvt_pk_bf16_f32 v120, v108, v109
	v_pk_mul_f32 v[128:129], v[128:129], v[66:67] op_sel_hi:[1,0]
	v_cvt_pk_bf16_f32 v121, v110, v111
	flat_load_dwordx4 v[108:111], v[70:71] offset:1024
	flat_load_dwordx4 v[112:115], v[72:73] offset:1024
	v_pk_mul_f32 v[130:131], v[130:131], v[66:67] op_sel_hi:[1,0]
	v_lshl_add_u64 v[124:125], v[68:69], 0, s[14:15]
	flat_store_dwordx2 v[124:125], v[120:121]
	v_pk_mul_f32 v[118:119], v[118:119], v[66:67] op_sel_hi:[1,0]
	v_pk_mul_f32 v[116:117], v[116:117], v[66:67] op_sel_hi:[1,0]
	v_mov_b32_e32 v11, v8
	s_mov_b64 s[14:15], -1
	s_waitcnt vmcnt(0) lgkmcnt(0)
	v_pk_fma_f32 v[110:111], v[110:111], v[130:131], v[114:115]
	v_pk_fma_f32 v[108:109], v[108:109], v[128:129], v[112:113]
	s_nop 0
	v_cvt_pk_bf16_f32 v120, v108, v109
	v_cvt_pk_bf16_f32 v121, v110, v111
	flat_load_dwordx4 v[108:111], v[70:71] offset:2048
	flat_load_dwordx4 v[112:115], v[72:73] offset:2048
	s_waitcnt vmcnt(0) lgkmcnt(0)
	v_pk_fma_f32 v[110:111], v[110:111], v[116:117], v[114:115]
	v_pk_fma_f32 v[108:109], v[108:109], v[118:119], v[112:113]
	flat_store_dwordx2 v[124:125], v[120:121] offset:512
	v_cvt_pk_bf16_f32 v116, v108, v109
	v_cvt_pk_bf16_f32 v117, v110, v111
	flat_load_dwordx4 v[108:111], v[70:71] offset:3072
	flat_load_dwordx4 v[112:115], v[72:73] offset:3072
	v_pk_mul_f32 v[118:119], v[26:27], v[66:67] op_sel_hi:[1,0]
	v_pk_mul_f32 v[120:121], v[28:29], v[66:67] op_sel_hi:[1,0]
	flat_store_dwordx2 v[124:125], v[116:117] offset:1024
	s_waitcnt vmcnt(0) lgkmcnt(0)
	v_pk_fma_f32 v[110:111], v[110:111], v[120:121], v[114:115]
	v_pk_fma_f32 v[108:109], v[108:109], v[118:119], v[112:113]
	v_pk_mul_f32 v[118:119], v[10:11], v[66:67] op_sel_hi:[1,0]
	v_cvt_pk_bf16_f32 v116, v108, v109
	v_cvt_pk_bf16_f32 v117, v110, v111
	flat_load_dwordx4 v[108:111], v[74:75]
	flat_load_dwordx4 v[112:115], v[76:77]
	v_pk_mul_f32 v[120:121], v[12:13], v[66:67] op_sel_hi:[1,0]
	flat_store_dwordx2 v[124:125], v[116:117] offset:1536
	s_waitcnt vmcnt(0) lgkmcnt(0)
	v_pk_fma_f32 v[110:111], v[110:111], v[120:121], v[114:115]
	v_pk_fma_f32 v[108:109], v[108:109], v[118:119], v[112:113]
	v_pk_mul_f32 v[118:119], v[126:127], v[66:67] op_sel_hi:[1,0]
	v_cvt_pk_bf16_f32 v116, v108, v109
	v_cvt_pk_bf16_f32 v117, v110, v111
	flat_load_dwordx4 v[108:111], v[78:79]
	flat_load_dwordx4 v[112:115], v[80:81]
	v_pk_mul_f32 v[120:121], v[122:123], v[66:67] op_sel_hi:[1,0]
	flat_store_dwordx2 v[124:125], v[116:117] offset:2048
	s_waitcnt vmcnt(0) lgkmcnt(0)
	v_pk_fma_f32 v[110:111], v[110:111], v[120:121], v[114:115]
	v_pk_fma_f32 v[108:109], v[108:109], v[118:119], v[112:113]
	v_pk_mul_f32 v[118:119], v[22:23], v[66:67] op_sel_hi:[1,0]
	v_cvt_pk_bf16_f32 v116, v108, v109
	v_cvt_pk_bf16_f32 v117, v110, v111
	flat_load_dwordx4 v[108:111], v[82:83]
	flat_load_dwordx4 v[112:115], v[84:85]
	v_pk_mul_f32 v[120:121], v[24:25], v[66:67] op_sel_hi:[1,0]
	flat_store_dwordx2 v[124:125], v[116:117] offset:2560
	s_waitcnt vmcnt(0) lgkmcnt(0)
	v_pk_fma_f32 v[110:111], v[120:121], v[110:111], v[114:115]
	v_pk_fma_f32 v[108:109], v[118:119], v[108:109], v[112:113]
	v_pk_mul_f32 v[118:119], v[18:19], v[66:67] op_sel_hi:[1,0]
	v_cvt_pk_bf16_f32 v116, v108, v109
	v_cvt_pk_bf16_f32 v117, v110, v111
	flat_load_dwordx4 v[108:111], v[86:87]
	flat_load_dwordx4 v[112:115], v[88:89]
	v_pk_mul_f32 v[120:121], v[20:21], v[66:67] op_sel_hi:[1,0]
	flat_store_dwordx2 v[124:125], v[116:117] offset:3072
	s_waitcnt vmcnt(0) lgkmcnt(0)
	v_pk_fma_f32 v[108:109], v[118:119], v[108:109], v[112:113]
	v_pk_fma_f32 v[110:111], v[120:121], v[110:111], v[114:115]
	v_cvt_pk_bf16_f32 v108, v108, v109
	s_nop 0
	v_cvt_pk_bf16_f32 v109, v110, v111
	flat_store_dwordx2 v[124:125], v[108:109] offset:3584
	s_cbranch_scc1 .LBB0_1452
	s_add_i32 s13, s12, s21
	s_cmpk_gt_i32 s13, 0x400f
	s_cselect_b64 s[14:15], -1, 0
	s_and_b64 vcc, exec, s[14:15]
	s_cbranch_vccnz .LBB0_1451
	s_ashr_i32 s18, s13, 31
	s_add_i32 s27, s13, -16
	s_cmp_gt_i32 s13, 15
	s_cselect_b32 s19, 0, s18
	s_cselect_b32 s18, s27, s13
	s_cselect_b32 s27, s9, s24
	s_cselect_b32 s28, s8, s23
	s_lshl_b64 s[18:19], s[18:19], 13
	s_add_u32 s18, s28, s18
	s_addc_u32 s19, s27, s19
	v_lshlrev_b32_e32 v66, 4, v62
	v_lshl_add_u64 v[90:91], s[18:19], 0, v[66:67]
	flat_load_dwordx4 v[2:5], v[90:91] nt
	flat_load_dwordx4 v[94:97], v[90:91] offset:1024 nt
	flat_load_dwordx4 v[6:9], v[90:91] offset:2048 nt
	v_add_co_u32_e32 v92, vcc, s25, v90
	s_mov_b32 s18, s13
	s_nop 0
	v_addc_co_u32_e32 v93, vcc, 0, v91, vcc
	flat_load_dwordx4 v[10:13], v[92:93] nt
	flat_load_dwordx4 v[14:17], v[92:93] offset:1024 nt
	flat_load_dwordx4 v[18:21], v[92:93] offset:3072 nt
	flat_load_dwordx4 v[22:25], v[92:93] offset:2048 nt
	flat_load_dwordx4 v[26:29], v[90:91] offset:3072 nt
	s_waitcnt vmcnt(0) lgkmcnt(0)
	v_mov_b32_e32 v91, v2
	v_mov_b32_e32 v93, v4
	v_mov_b32_e32 v90, v94
	v_mov_b32_e32 v2, v95
	v_mov_b32_e32 v92, v96
	v_mov_b32_e32 v4, v97
	v_mov_b32_e32 v94, v7
	v_mov_b32_e32 v95, v8
	v_mov_b32_e32 v7, v9
	v_mov_b32_e32 v8, v11
	v_mov_b32_e32 v96, v13
	v_mov_b32_e32 v98, v15
	v_mov_b32_e32 v99, v16
	v_mov_b32_e32 v15, v17
	v_mov_b32_e32 v16, v19
	v_mov_b32_e32 v100, v21
	s_branch .LBB0_1451

; #define PH_BEGIN const Params P = load_params(); unsigned char* ws = P.ws;
; __device__ __forceinline__ void ln_load(f32x4 (&v)[8], const float* z, int lane) {
; #pragma unroll
;     for (int j = 0; j < 8; ++j) v[j] = ((const f32x4*)z)[lane + 64 * j];
; }
; template <int L, int K>
; __device__ __forceinline__ void phase_body(char* lds, int rep_) {
;     ...
;     if constexpr (K == 5) { PH_BEGIN
;         const float* g1 = P.in[11] + L * DM; const float* b1 = P.in[12] + L * DM; const float* Z1 = (const float*)(ws + WS_Z1); bf16_t* HB = (bf16_t*)(ws + WS_HB);
;         const float* lg_ = g1; const float* lb_ = b1;
;     ...
;         LN_ROWS(gw, LTOK, NGW, ZR_, HR_, FR_);
.LBB0_2622:
	s_cmp_lt_i32 s80, 16
	s_cselect_b64 s[6:7], -1, 0
	s_and_b64 s[8:9], s[6:7], s[40:41]
	s_andn2_b64 vcc, exec, s[8:9]
	s_cbranch_vccnz .LBB0_2632
	v_mov_b32_e32 v1, v194
	s_lshl_b32 s8, s2, 3
	v_readfirstlane_b32 s3, v1
	s_ashr_i32 s3, s3, 6
	s_add_i32 s8, s3, s8
	s_mov_b64 s[12:13], s[0:1]
	s_cmpk_gt_i32 s8, 0x400f
	s_cbranch_scc1 .LBB0_2632
	s_load_dword s3, s[0:1], 0xa0
	s_load_dwordx2 s[10:11], s[12:13], 0x90
	s_load_dwordx4 s[20:23], s[12:13], 0x58
	v_and_b32_e32 v98, 63, v1
	v_lshlrev_b32_e32 v96, 4, v98
	s_waitcnt lgkmcnt(0)
	s_lshl_b32 s3, s3, 3
	s_add_u32 s16, s10, 0xeb00000
	s_addc_u32 s17, s11, 0
	s_add_u32 s12, s22, 0x2000
	s_addc_u32 s13, s23, 0
	s_add_u32 s14, s20, 0x2000
	s_addc_u32 s15, s21, 0
	s_ashr_i32 s9, s8, 31
	s_lshl_b64 s[18:19], s[8:9], 13
	s_add_u32 s18, s16, s18
	s_addc_u32 s19, s17, s19
	v_mov_b32_e32 v97, 0
	v_lshl_add_u64 v[30:31], s[18:19], 0, v[96:97]
	s_movk_i32 s9, 0x1000
	v_add_co_u32_e32 v32, vcc, s9, v30
	flat_load_dwordx4 v[2:5], v[30:31] nt
	flat_load_dwordx4 v[102:105], v[30:31] offset:1024 nt
	flat_load_dwordx4 v[6:9], v[30:31] offset:2048 nt
	v_addc_co_u32_e32 v33, vcc, 0, v31, vcc
	flat_load_dwordx4 v[10:13], v[32:33] nt
	flat_load_dwordx4 v[14:17], v[32:33] offset:1024 nt
	flat_load_dwordx4 v[18:21], v[32:33] offset:2048 nt
	flat_load_dwordx4 v[22:25], v[32:33] offset:3072 nt
	flat_load_dwordx4 v[26:29], v[30:31] offset:3072 nt
	v_mbcnt_lo_u32_b32 v62, -1, 0
	v_mbcnt_hi_u32_b32 v62, -1, v62
	v_and_b32_e32 v63, 64, v62
	v_xor_b32_e32 v64, 1, v62
	v_add_u32_e32 v63, 64, v63
	v_xor_b32_e32 v65, 2, v62
	v_cmp_lt_i32_e32 vcc, v64, v63
	v_xor_b32_e32 v66, 4, v62
	v_xor_b32_e32 v67, 8, v62
	v_cndmask_b32_e32 v64, v62, v64, vcc
	v_cmp_lt_i32_e32 vcc, v65, v63
	v_xor_b32_e32 v68, 16, v62
	v_xor_b32_e32 v69, 32, v62
	v_cndmask_b32_e32 v65, v62, v65, vcc
	v_cmp_lt_i32_e32 vcc, v66, v63
	v_or_b32_e32 v80, 0x400, v96
	v_or_b32_e32 v82, 0x800, v96
	v_cndmask_b32_e32 v66, v62, v66, vcc
	v_cmp_lt_i32_e32 vcc, v67, v63
	v_or_b32_e32 v84, 0xc00, v96
	v_or_b32_e32 v86, 0x1000, v96
	v_cndmask_b32_e32 v67, v62, v67, vcc
	v_cmp_lt_i32_e32 vcc, v68, v63
	v_or_b32_e32 v88, 0x1400, v96
	v_or_b32_e32 v90, 0x1800, v96
	v_cndmask_b32_e32 v68, v62, v68, vcc
	v_cmp_lt_i32_e32 vcc, v69, v63
	v_lshlrev_b32_e32 v110, 2, v64
	v_lshlrev_b32_e32 v111, 2, v65
	v_cndmask_b32_e32 v62, v62, v69, vcc
	v_lshlrev_b32_e32 v115, 2, v62
	v_lshl_add_u64 v[62:63], s[16:17], 0, v[96:97]
	v_lshl_add_u64 v[64:65], s[12:13], 0, v[96:97]
	v_lshl_add_u64 v[78:79], s[14:15], 0, v[96:97]
	v_or_b32_e32 v96, 0x1c00, v96
	v_lshl_add_u64 v[92:93], s[14:15], 0, v[96:97]
	v_lshl_add_u64 v[94:95], s[12:13], 0, v[96:97]
	v_lshlrev_b32_e32 v96, 3, v98
	s_mov_b64 s[20:21], 0x6900000
	v_mov_b32_e32 v81, v97
	v_mov_b32_e32 v83, v97
	v_mov_b32_e32 v85, v97
	v_mov_b32_e32 v87, v97
	v_mov_b32_e32 v89, v97
	v_mov_b32_e32 v91, v97
	v_lshl_add_u64 v[96:97], s[10:11], 0, v[96:97]
	v_mov_b32_e32 v1, 0x3727c5ac
	s_mov_b32 s18, 0x800000
	v_lshlrev_b32_e32 v112, 2, v66
	v_lshlrev_b32_e32 v113, 2, v67
	v_lshlrev_b32_e32 v114, 2, v68
	v_lshl_add_u64 v[66:67], s[12:13], 0, v[80:81]
	v_lshl_add_u64 v[68:69], s[12:13], 0, v[82:83]
	v_lshl_add_u64 v[70:71], s[12:13], 0, v[84:85]
	v_lshl_add_u64 v[72:73], s[12:13], 0, v[86:87]
	v_lshl_add_u64 v[74:75], s[12:13], 0, v[88:89]
	v_lshl_add_u64 v[76:77], s[12:13], 0, v[90:91]
	v_lshl_add_u64 v[80:81], s[14:15], 0, v[80:81]
	v_lshl_add_u64 v[82:83], s[14:15], 0, v[82:83]
	v_lshl_add_u64 v[84:85], s[14:15], 0, v[84:85]
	v_lshl_add_u64 v[86:87], s[14:15], 0, v[86:87]
	v_lshl_add_u64 v[88:89], s[14:15], 0, v[88:89]
	v_lshl_add_u64 v[90:91], s[14:15], 0, v[90:91]
	v_lshl_add_u64 v[96:97], v[96:97], 0, s[20:21]
	s_waitcnt vmcnt(0) lgkmcnt(0)
	v_mov_b32_e32 v99, v2
	v_mov_b32_e32 v101, v4
	v_mov_b32_e32 v98, v102
	v_mov_b32_e32 v2, v103
	v_mov_b32_e32 v100, v104
	v_mov_b32_e32 v4, v105
	v_mov_b32_e32 v102, v7
	v_mov_b32_e32 v103, v8
	v_mov_b32_e32 v7, v9
	v_mov_b32_e32 v8, v11
	v_mov_b32_e32 v104, v13
	v_mov_b32_e32 v106, v15
	v_mov_b32_e32 v107, v16
	v_mov_b32_e32 v15, v17
	v_mov_b32_e32 v16, v23
	v_mov_b32_e32 v108, v25
	s_branch .LBB0_2627

; __device__ __forceinline__ void ln_apply(f32x4 (&v)[8], const float* __restrict__ g, const float* __restrict__ b, bf16_t* hb, float* fo, int lane) {
;     float s = 0.f;
; #pragma unroll
;     for (int j = 0; j < 8; ++j) s += (v[j][0] + v[j][1]) + (v[j][2] + v[j][3]);
;     const float mean = wave_sum(s) * (1.f / DM); float q = 0.f;
; #pragma unroll
;     for (int j = 0; j < 8; ++j) { v[j] = v[j] - mean; q += (v[j][0] * v[j][0] + v[j][1] * v[j][1]) + (v[j][2] * v[j][2] + v[j][3] * v[j][3]); }
;     const float rstd = rsqrtf(wave_sum(q) * (1.f / DM) + LN_EPS);
.LBB0_2627:
	s_add_i32 s10, s8, s3
	s_cmpk_gt_i32 s10, 0x400f
	s_cbranch_scc1 .LBB0_2629
	s_ashr_i32 s11, s10, 31
	s_lshl_b64 s[12:13], s[10:11], 13
	v_lshl_add_u64 v[46:47], v[62:63], 0, s[12:13]
	v_add_co_u32_e32 v116, vcc, 0x1000, v46
	flat_load_dwordx4 v[42:45], v[46:47] nt
	flat_load_dwordx4 v[38:41], v[46:47] offset:1024 nt
	flat_load_dwordx4 v[34:37], v[46:47] offset:2048 nt
	flat_load_dwordx4 v[30:33], v[46:47] offset:3072 nt
	v_addc_co_u32_e32 v117, vcc, 0, v47, vcc
	flat_load_dwordx4 v[58:61], v[116:117] nt
	flat_load_dwordx4 v[54:57], v[116:117] offset:1024 nt
	flat_load_dwordx4 v[50:53], v[116:117] offset:2048 nt
	flat_load_dwordx4 v[46:49], v[116:117] offset:3072 nt
.LBB0_2629:
	v_pk_add_f32 v[116:117], v[98:99], v[2:3]
	v_pk_add_f32 v[118:119], v[100:101], v[4:5]
	v_add_f32_e32 v11, v26, v27
	v_pk_add_f32 v[116:117], v[116:117], v[118:119]
	v_add_f32_e32 v23, v18, v19
	v_add_f32_e32 v9, 0, v117
	v_add_f32_e32 v105, v116, v9
	v_pk_add_f32 v[116:117], v[102:103], v[6:7]
	v_add_f32_e32 v9, v28, v29
	v_pk_add_f32 v[116:117], v[116:117], v[116:117] op_sel_hi:[0,1]
	v_mov_b32_e32 v13, v117
	v_pk_add_f32 v[118:119], v[10:11], v[8:9]
	v_pk_add_f32 v[116:117], v[12:13], v[104:105]
	v_add_f32_e32 v17, v20, v21
	v_pk_add_f32 v[116:117], v[118:119], v[116:117]
	v_pk_add_f32 v[118:119], v[106:107], v[14:15]
	v_pk_add_f32 v[116:117], v[116:117], v[116:117] op_sel_hi:[0,1]
	v_pk_add_f32 v[118:119], v[118:119], v[118:119] op_sel_hi:[0,1]
	v_mov_b32_e32 v25, v119
	v_mov_b32_e32 v109, v117
	v_pk_add_f32 v[120:121], v[22:23], v[16:17]
	v_pk_add_f32 v[116:117], v[24:25], v[108:109]
	s_ashr_i32 s9, s8, 31
	v_pk_add_f32 v[116:117], v[120:121], v[116:117]
	s_lshl_b64 s[12:13], s[8:9], 12
	v_add_f32_e32 v9, v116, v117
	ds_bpermute_b32 v11, v110, v9
	s_cmpk_gt_i32 s10, 0x400f
	s_waitcnt lgkmcnt(0)
	v_add_f32_e32 v9, v9, v11
	ds_bpermute_b32 v11, v111, v9
	s_waitcnt lgkmcnt(0)
	v_add_f32_e32 v9, v9, v11
	ds_bpermute_b32 v11, v112, v9
	s_waitcnt lgkmcnt(0)
	v_add_f32_e32 v9, v9, v11
	ds_bpermute_b32 v11, v113, v9
	s_waitcnt lgkmcnt(0)
	v_add_f32_e32 v9, v9, v11
	ds_bpermute_b32 v11, v114, v9
	s_waitcnt lgkmcnt(0)
	v_add_f32_e32 v9, v9, v11
	ds_bpermute_b32 v11, v115, v9
	s_waitcnt lgkmcnt(0)
	v_add_f32_e32 v9, v9, v11
	v_fmac_f32_e32 v3, 0xba000000, v9
	v_fmac_f32_e32 v2, 0xba000000, v9
	v_fmac_f32_e32 v99, 0xba000000, v9
	v_fmac_f32_e32 v98, 0xba000000, v9
	v_mov_b32_e32 v118, v3
	v_mov_b32_e32 v119, v2
	v_fmac_f32_e32 v5, 0xba000000, v9
	v_fmac_f32_e32 v4, 0xba000000, v9
	v_mov_b32_e32 v116, v99
	v_mov_b32_e32 v117, v98
	v_pk_mul_f32 v[118:119], v[118:119], v[118:119]
	v_fmac_f32_e32 v101, 0xba000000, v9
	v_fmac_f32_e32 v100, 0xba000000, v9
	v_pk_fma_f32 v[116:117], v[116:117], v[116:117], v[118:119]
	v_mov_b32_e32 v118, v5
	v_mov_b32_e32 v119, v4
	v_mov_b32_e32 v120, v101
	v_mov_b32_e32 v121, v100
	v_pk_mul_f32 v[118:119], v[118:119], v[118:119]
	v_fmac_f32_e32 v7, 0xba000000, v9
	v_pk_fma_f32 v[118:119], v[120:121], v[120:121], v[118:119]
	v_fmac_f32_e32 v103, 0xba000000, v9
	v_fmac_f32_e32 v102, 0xba000000, v9
	v_fmac_f32_e32 v6, 0xba000000, v9
	v_pk_add_f32 v[116:117], v[116:117], v[118:119]
	v_mov_b32_e32 v124, v103
	v_mov_b32_e32 v125, v7
	v_mov_b32_e32 v126, v6
	v_mov_b32_e32 v127, v102
	v_pk_add_f32 v[116:117], v[116:117], v[116:117] op_sel_hi:[0,1]
	v_pk_mul_f32 v[118:119], v[124:125], v[124:125]
	v_pk_mul_f32 v[120:121], v[126:127], v[126:127]
	v_fmac_f32_e32 v26, 0xba000000, v9
	v_pk_mov_b32 v[122:123], v[120:121], v[118:119] op_sel:[1,0]
	v_mov_b32_e32 v121, v119
	v_fmac_f32_e32 v28, 0xba000000, v9
	v_fmac_f32_e32 v27, 0xba000000, v9
	v_mul_f32_e32 v116, v26, v26
	v_pk_add_f32 v[118:119], v[122:123], v[120:121]
	v_fmac_f32_e32 v29, 0xba000000, v9
	v_pk_fma_f32 v[120:121], v[26:27], v[26:27], v[116:117] op_sel_hi:[1,1,0]
	v_mul_f32_e32 v116, v28, v28
	v_pk_add_f32 v[118:119], v[118:119], v[118:119] op_sel_hi:[0,1]
	v_pk_fma_f32 v[122:123], v[28:29], v[28:29], v[116:117] op_sel_hi:[1,1,0]
	v_fmac_f32_e32 v104, 0xba000000, v9
	v_fmac_f32_e32 v12, 0xba000000, v9
	v_fmac_f32_e32 v8, 0xba000000, v9
	v_fmac_f32_e32 v10, 0xba000000, v9
	v_mul_f32_e32 v120, v10, v10
	v_mul_f32_e32 v122, v8, v8
	v_mul_f32_e32 v118, v12, v12
	v_mul_f32_e32 v116, v104, v104
	v_pk_add_f32 v[120:121], v[120:121], v[122:123]
	v_pk_add_f32 v[116:117], v[118:119], v[116:117]
	v_fmac_f32_e32 v15, 0xba000000, v9
	v_pk_add_f32 v[116:117], v[120:121], v[116:117]
	v_fmac_f32_e32 v107, 0xba000000, v9
	v_pk_add_f32 v[128:129], v[116:117], v[116:117] op_sel_hi:[0,1]
	flat_load_dwordx4 v[116:119], v[78:79]
	flat_load_dwordx4 v[120:123], v[64:65]
	v_fmac_f32_e32 v106, 0xba000000, v9
	v_fmac_f32_e32 v14, 0xba000000, v9
	v_mov_b32_e32 v130, v107
	v_mov_b32_e32 v131, v15
	v_mov_b32_e32 v134, v14
	v_mov_b32_e32 v135, v106
	v_pk_mul_f32 v[132:133], v[130:131], v[130:131]
	v_pk_mul_f32 v[136:137], v[134:135], v[134:135]
	v_fmac_f32_e32 v18, 0xba000000, v9
	v_pk_mov_b32 v[138:139], v[136:137], v[132:133] op_sel:[1,0]
	v_mov_b32_e32 v137, v133
	v_fmac_f32_e32 v20, 0xba000000, v9
	v_fmac_f32_e32 v19, 0xba000000, v9
	v_mul_f32_e32 v128, v18, v18
	v_pk_add_f32 v[132:133], v[138:139], v[136:137]
	v_fmac_f32_e32 v21, 0xba000000, v9
	v_pk_fma_f32 v[136:137], v[18:19], v[18:19], v[128:129] op_sel_hi:[1,1,0]
	v_mul_f32_e32 v128, v20, v20
	v_pk_add_f32 v[132:133], v[132:133], v[132:133] op_sel_hi:[0,1]
	v_pk_fma_f32 v[138:139], v[20:21], v[20:21], v[128:129] op_sel_hi:[1,1,0]
	v_fmac_f32_e32 v108, 0xba000000, v9
	v_fmac_f32_e32 v24, 0xba000000, v9
	v_fmac_f32_e32 v16, 0xba000000, v9
	v_fmac_f32_e32 v22, 0xba000000, v9
	v_mul_f32_e32 v136, v22, v22
	v_mul_f32_e32 v138, v16, v16
	v_mul_f32_e32 v132, v24, v24
	v_mul_f32_e32 v128, v108, v108
	v_pk_add_f32 v[136:137], v[136:137], v[138:139]
	v_pk_add_f32 v[128:129], v[132:133], v[128:129]
	v_mov_b32_e32 v132, v101
	v_pk_add_f32 v[128:129], v[136:137], v[128:129]
	v_mov_b32_e32 v133, v5
	v_add_f32_e32 v9, v128, v129
	ds_bpermute_b32 v11, v110, v9
	v_mov_b32_e32 v128, v99
	v_mov_b32_e32 v129, v3
	v_mov_b32_e32 v138, v98
	v_mov_b32_e32 v139, v2
	s_waitcnt lgkmcnt(0)
; __device__ __forceinline__ unsigned cvt_pk_bf16(float lo, float hi) { unsigned r; asm volatile("v_cvt_pk_bf16_f32 %0, %1, %2" : "=v"(r) : "v"(lo), "v"(hi)); return r; }
; __device__ __forceinline__ void ln_apply(f32x4 (&v)[8], const float* __restrict__ g, const float* __restrict__ b, bf16_t* hb, float* fo, int lane) {
;     ...
;     const float rstd = rsqrtf(wave_sum(q) * (1.f / DM) + LN_EPS);
; #pragma unroll
;     for (int j = 0; j < 8; ++j) { const int c = (lane + 64 * j) * 4; const f32x4 gg = *(const f32x4*)(g + c), bb = *(const f32x4*)(b + c);
;         const f32x4 y = v[j] * rstd * gg + bb;
;         if (hb) { u32x2 w; w.x = cvt_pk_bf16(y[0], y[1]); w.y = cvt_pk_bf16(y[2], y[3]); *(u32x2*)(hb + c) = w; }
;         if (fo) *(f32x4*)(fo + c) = y; }
	v_add_f32_e32 v9, v9, v11
	ds_bpermute_b32 v11, v111, v9
	v_mov_b32_e32 v140, v100
	v_mov_b32_e32 v141, v4
	v_mov_b32_e32 v13, v104
	v_mov_b32_e32 v23, v16
	s_waitcnt lgkmcnt(0)
	v_add_f32_e32 v9, v9, v11
	ds_bpermute_b32 v11, v112, v9
	v_mov_b32_e32 v25, v108
	s_waitcnt lgkmcnt(0)
	v_add_f32_e32 v9, v9, v11
	ds_bpermute_b32 v11, v113, v9
	s_waitcnt lgkmcnt(0)
	v_add_f32_e32 v9, v9, v11
	ds_bpermute_b32 v11, v114, v9
	s_waitcnt lgkmcnt(0)
	v_add_f32_e32 v9, v9, v11
	ds_bpermute_b32 v11, v115, v9
	s_waitcnt lgkmcnt(0)
	v_add_f32_e32 v9, v9, v11
	v_fmamk_f32 v9, v9, 0x3a000000, v1
	v_mul_f32_e32 v11, 0x4b800000, v9
	v_cmp_gt_f32_e32 vcc, s18, v9
	s_nop 1
	v_cndmask_b32_e32 v9, v9, v11, vcc
	v_rsq_f32_e32 v9, v9
	s_nop 0
	v_mul_f32_e32 v11, 0x45800000, v9
	v_cndmask_b32_e32 v136, v9, v11, vcc
	v_pk_mul_f32 v[128:129], v[128:129], v[136:137] op_sel_hi:[1,0]
	v_pk_mul_f32 v[132:133], v[132:133], v[136:137] op_sel_hi:[1,0]
	s_waitcnt vmcnt(0)
	v_pk_fma_f32 v[116:117], v[116:117], v[128:129], v[120:121]
	v_pk_fma_f32 v[118:119], v[118:119], v[132:133], v[122:123]
	v_cvt_pk_bf16_f32 v128, v116, v117
	v_pk_mul_f32 v[138:139], v[138:139], v[136:137] op_sel_hi:[1,0]
	v_cvt_pk_bf16_f32 v129, v118, v119
	flat_load_dwordx4 v[116:119], v[80:81]
	flat_load_dwordx4 v[120:123], v[66:67]
	v_pk_mul_f32 v[140:141], v[140:141], v[136:137] op_sel_hi:[1,0]
	v_lshl_add_u64 v[132:133], v[96:97], 0, s[12:13]
	flat_store_dwordx2 v[132:133], v[128:129]
	v_pk_mul_f32 v[126:127], v[126:127], v[136:137] op_sel_hi:[1,0]
	v_pk_mul_f32 v[124:125], v[124:125], v[136:137] op_sel_hi:[1,0]
	v_mov_b32_e32 v11, v8
	s_mov_b64 s[12:13], -1
	s_waitcnt vmcnt(0) lgkmcnt(0)
	v_pk_fma_f32 v[118:119], v[118:119], v[140:141], v[122:123]
	v_pk_fma_f32 v[116:117], v[116:117], v[138:139], v[120:121]
	s_nop 0
	v_cvt_pk_bf16_f32 v128, v116, v117
	v_cvt_pk_bf16_f32 v129, v118, v119
	flat_load_dwordx4 v[116:119], v[82:83]
	flat_load_dwordx4 v[120:123], v[68:69]
	s_waitcnt vmcnt(0) lgkmcnt(0)
	v_pk_fma_f32 v[118:119], v[118:119], v[124:125], v[122:123]
	v_pk_fma_f32 v[116:117], v[116:117], v[126:127], v[120:121]
	flat_store_dwordx2 v[132:133], v[128:129] offset:512
	v_cvt_pk_bf16_f32 v124, v116, v117
	v_cvt_pk_bf16_f32 v125, v118, v119
	flat_load_dwordx4 v[116:119], v[84:85]
	flat_load_dwordx4 v[120:123], v[70:71]
	v_pk_mul_f32 v[126:127], v[26:27], v[136:137] op_sel_hi:[1,0]
	v_pk_mul_f32 v[128:129], v[28:29], v[136:137] op_sel_hi:[1,0]
	flat_store_dwordx2 v[132:133], v[124:125] offset:1024
	s_waitcnt vmcnt(0) lgkmcnt(0)
	v_pk_fma_f32 v[118:119], v[118:119], v[128:129], v[122:123]
	v_pk_fma_f32 v[116:117], v[116:117], v[126:127], v[120:121]
	v_pk_mul_f32 v[126:127], v[10:11], v[136:137] op_sel_hi:[1,0]
	v_cvt_pk_bf16_f32 v124, v116, v117
	v_cvt_pk_bf16_f32 v125, v118, v119
	flat_load_dwordx4 v[116:119], v[86:87]
	flat_load_dwordx4 v[120:123], v[72:73]
	v_pk_mul_f32 v[128:129], v[12:13], v[136:137] op_sel_hi:[1,0]
	flat_store_dwordx2 v[132:133], v[124:125] offset:1536
	s_waitcnt vmcnt(0) lgkmcnt(0)
	v_pk_fma_f32 v[118:119], v[118:119], v[128:129], v[122:123]
	v_pk_fma_f32 v[116:117], v[116:117], v[126:127], v[120:121]
	v_pk_mul_f32 v[126:127], v[134:135], v[136:137] op_sel_hi:[1,0]
	v_cvt_pk_bf16_f32 v124, v116, v117
	v_cvt_pk_bf16_f32 v125, v118, v119
	flat_load_dwordx4 v[116:119], v[88:89]
	flat_load_dwordx4 v[120:123], v[74:75]
	v_pk_mul_f32 v[128:129], v[130:131], v[136:137] op_sel_hi:[1,0]
	flat_store_dwordx2 v[132:133], v[124:125] offset:2048
	s_waitcnt vmcnt(0) lgkmcnt(0)
	v_pk_fma_f32 v[118:119], v[118:119], v[128:129], v[122:123]
	v_pk_fma_f32 v[116:117], v[116:117], v[126:127], v[120:121]
	v_pk_mul_f32 v[126:127], v[18:19], v[136:137] op_sel_hi:[1,0]
	v_cvt_pk_bf16_f32 v124, v116, v117
	v_cvt_pk_bf16_f32 v125, v118, v119
	flat_load_dwordx4 v[116:119], v[90:91]
	flat_load_dwordx4 v[120:123], v[76:77]
	v_pk_mul_f32 v[128:129], v[20:21], v[136:137] op_sel_hi:[1,0]
	flat_store_dwordx2 v[132:133], v[124:125] offset:2560
	s_waitcnt vmcnt(0) lgkmcnt(0)
	v_pk_fma_f32 v[118:119], v[128:129], v[118:119], v[122:123]
	v_pk_fma_f32 v[116:117], v[126:127], v[116:117], v[120:121]
	v_pk_mul_f32 v[126:127], v[22:23], v[136:137] op_sel_hi:[1,0]
	v_cvt_pk_bf16_f32 v124, v116, v117
	v_cvt_pk_bf16_f32 v125, v118, v119
	flat_load_dwordx4 v[116:119], v[92:93]
	flat_load_dwordx4 v[120:123], v[94:95]
	v_pk_mul_f32 v[128:129], v[24:25], v[136:137] op_sel_hi:[1,0]
	flat_store_dwordx2 v[132:133], v[124:125] offset:3072
	s_waitcnt vmcnt(0) lgkmcnt(0)
	v_pk_fma_f32 v[116:117], v[126:127], v[116:117], v[120:121]
	v_pk_fma_f32 v[118:119], v[128:129], v[118:119], v[122:123]
	v_cvt_pk_bf16_f32 v116, v116, v117
	s_nop 0
	v_cvt_pk_bf16_f32 v117, v118, v119
	flat_store_dwordx2 v[132:133], v[116:117] offset:3584
	s_cbranch_scc1 .LBB0_2626
	s_add_i32 s14, s10, s3
	s_cmpk_gt_i32 s14, 0x400f
	s_cselect_b64 s[12:13], -1, 0
	s_and_b64 vcc, exec, s[12:13]
	s_cbranch_vccnz .LBB0_2625
	s_ashr_i32 s15, s14, 31
	s_lshl_b64 s[8:9], s[14:15], 13
	v_lshl_add_u64 v[98:99], v[62:63], 0, s[8:9]
	flat_load_dwordx4 v[2:5], v[98:99] nt
	flat_load_dwordx4 v[102:105], v[98:99] offset:1024 nt
	flat_load_dwordx4 v[6:9], v[98:99] offset:2048 nt
	v_add_co_u32_e32 v100, vcc, 0x1000, v98
	s_mov_b32 s8, s14
	s_nop 0
	v_addc_co_u32_e32 v101, vcc, 0, v99, vcc
	flat_load_dwordx4 v[10:13], v[100:101] nt
	flat_load_dwordx4 v[14:17], v[100:101] offset:1024 nt
	flat_load_dwordx4 v[22:25], v[100:101] offset:3072 nt
	flat_load_dwordx4 v[18:21], v[100:101] offset:2048 nt
	flat_load_dwordx4 v[26:29], v[98:99] offset:3072 nt
	s_waitcnt vmcnt(0) lgkmcnt(0)
	v_mov_b32_e32 v99, v2
	v_mov_b32_e32 v101, v4
	v_mov_b32_e32 v98, v102
	v_mov_b32_e32 v2, v103
	v_mov_b32_e32 v100, v104
	v_mov_b32_e32 v4, v105
	v_mov_b32_e32 v102, v7
	v_mov_b32_e32 v103, v8
	v_mov_b32_e32 v7, v9
	v_mov_b32_e32 v8, v11
	v_mov_b32_e32 v104, v13
	v_mov_b32_e32 v106, v15
	v_mov_b32_e32 v107, v16
	v_mov_b32_e32 v15, v17
	v_mov_b32_e32 v16, v23
	v_mov_b32_e32 v108, v25
	s_branch .LBB0_2625

; __device__ __forceinline__ void ln_load(f32x4 (&v)[8], const float* z, int lane) {
; #pragma unroll
;     for (int j = 0; j < 8; ++j) v[j] = ((const f32x4*)z)[lane + 64 * j];
; }
; template <int L, int K>
; __device__ __forceinline__ void phase_body(char* lds, int rep_) {
;     ...
;         } else {
;             const float* lg_ = g2; const float* lb_ = b2;
;     ...
;             LN_ROWS(gw + NMETA, LTOK, NGW, ZR_, HR_, FR_);
.LBB0_2876:
	s_cmp_lt_i32 s80, 19
	s_cselect_b64 s[4:5], -1, 0
	s_and_b64 s[4:5], s[4:5], s[36:37]
	s_andn2_b64 vcc, exec, s[4:5]
	s_cbranch_vccnz .LBB0_2889
	s_lshl_b32 s2, s2, 3
	v_readfirstlane_b32 s3, v194
	s_ashr_i32 s3, s3, 6
	s_add_i32 s2, s3, s2
	s_mov_b64 s[6:7], s[0:1]
	s_cmpk_gt_i32 s2, 0x3fff
	s_cbranch_scc1 .LBB0_2889
	s_load_dword s10, s[0:1], 0xa0
	s_load_dwordx4 s[16:19], s[6:7], 0x78
	s_load_dwordx2 s[4:5], s[6:7], 0x88
	v_and_b32_e32 v66, 63, v194
	v_lshlrev_b32_e32 v64, 4, v66
	s_waitcnt lgkmcnt(0)
	s_lshl_b32 s12, s10, 3
	s_add_u32 s0, s18, 0x2000
	s_addc_u32 s1, s19, 0
	s_add_u32 s8, s16, 0x2000
	s_addc_u32 s9, s17, 0
	s_ashr_i32 s3, s2, 31
	s_lshl_b64 s[6:7], s[2:3], 13
	s_add_u32 s6, s4, s6
	s_addc_u32 s7, s5, s7
	v_mov_b32_e32 v65, 0
	v_lshl_add_u64 v[32:33], s[6:7], 0, v[64:65]
	s_movk_i32 s3, 0x1000
	v_add_co_u32_e32 v34, vcc, s3, v32
	flat_load_dwordx4 v[0:3], v[32:33] nt
	flat_load_dwordx4 v[4:7], v[32:33] offset:1024 nt
	flat_load_dwordx4 v[8:11], v[32:33] offset:2048 nt
	v_addc_co_u32_e32 v35, vcc, 0, v33, vcc
	flat_load_dwordx4 v[12:15], v[34:35] nt
	flat_load_dwordx4 v[16:19], v[34:35] offset:1024 nt
	flat_load_dwordx4 v[20:23], v[34:35] offset:2048 nt
	flat_load_dwordx4 v[24:27], v[34:35] offset:3072 nt
	flat_load_dwordx4 v[28:31], v[32:33] offset:3072 nt
	v_mbcnt_lo_u32_b32 v68, -1, 0
	v_mbcnt_hi_u32_b32 v69, -1, v68
	v_and_b32_e32 v71, 64, v69
	v_xor_b32_e32 v73, 1, v69
	v_add_u32_e32 v71, 64, v71
	v_xor_b32_e32 v75, 2, v69
	v_cmp_lt_i32_e32 vcc, v73, v71
	v_xor_b32_e32 v76, 4, v69
	v_xor_b32_e32 v77, 8, v69
	v_cndmask_b32_e32 v73, v69, v73, vcc
	v_cmp_lt_i32_e32 vcc, v75, v71
	v_xor_b32_e32 v78, 16, v69
	v_xor_b32_e32 v79, 32, v69
	v_cndmask_b32_e32 v75, v69, v75, vcc
	v_cmp_lt_i32_e32 vcc, v76, v71
	v_lshlrev_b32_e32 v66, 2, v66
	v_or_b32_e32 v86, 0x400, v64
	v_cndmask_b32_e32 v80, v69, v76, vcc
	v_cmp_lt_i32_e32 vcc, v77, v71
	v_or_b32_e32 v88, 0x800, v64
	v_or_b32_e32 v68, 0x400, v66
	v_cndmask_b32_e32 v81, v69, v77, vcc
	v_cmp_lt_i32_e32 vcc, v78, v71
	v_lshl_add_u64 v[76:77], s[4:5], 0, v[64:65]
	v_lshl_add_u64 v[84:85], s[8:9], 0, v[64:65]
	v_cndmask_b32_e32 v78, v69, v78, vcc
	v_cmp_lt_i32_e32 vcc, v79, v71
	v_lshlrev_b32_e32 v118, 2, v78
	v_or_b32_e32 v70, 0x500, v66
	v_cndmask_b32_e32 v79, v69, v79, vcc
	v_lshlrev_b32_e32 v119, 2, v79
	v_lshl_add_u64 v[78:79], s[0:1], 0, v[64:65]
	v_or_b32_e32 v64, 0xc00, v64
	v_lshl_add_u64 v[90:91], s[8:9], 0, v[64:65]
	v_lshl_add_u64 v[92:93], s[0:1], 0, v[64:65]
	v_lshlrev_b32_e32 v64, 2, v68
	v_or_b32_e32 v72, 0x600, v66
	v_lshl_add_u64 v[94:95], s[8:9], 0, v[64:65]
	v_lshl_add_u64 v[96:97], s[0:1], 0, v[64:65]
	v_lshlrev_b32_e32 v64, 2, v70
	v_or_b32_e32 v74, 0x700, v66
	v_lshl_add_u64 v[98:99], s[8:9], 0, v[64:65]
	v_lshl_add_u64 v[100:101], s[0:1], 0, v[64:65]
	v_lshlrev_b32_e32 v64, 2, v72
	v_mov_b32_e32 v87, v65
	v_mov_b32_e32 v89, v65
	s_cmp_lg_u64 s[4:5], 0
	v_lshl_add_u64 v[102:103], s[8:9], 0, v[64:65]
	v_lshl_add_u64 v[104:105], s[0:1], 0, v[64:65]
	v_lshlrev_b32_e32 v64, 2, v74
	v_mov_b32_e32 v67, 0x3727c5ac
	s_mov_b32 s13, 0x800000
	v_lshlrev_b32_e32 v69, 2, v73
	v_lshlrev_b32_e32 v71, 2, v75
	v_lshlrev_b32_e32 v73, 2, v80
	v_lshlrev_b32_e32 v75, 2, v81
	v_lshl_add_u64 v[80:81], s[0:1], 0, v[86:87]
	v_lshl_add_u64 v[82:83], s[0:1], 0, v[88:89]
	v_lshl_add_u64 v[86:87], s[8:9], 0, v[86:87]
	v_lshl_add_u64 v[88:89], s[8:9], 0, v[88:89]
	s_cselect_b64 s[6:7], -1, 0
	s_lshl_b32 s14, s10, 4
	v_lshl_add_u64 v[106:107], s[8:9], 0, v[64:65]
	v_lshl_add_u64 v[108:109], s[0:1], 0, v[64:65]
	s_waitcnt vmcnt(0) lgkmcnt(0)
	v_mov_b32_e32 v111, v2
	v_mov_b32_e32 v110, v6
	v_mov_b32_e32 v2, v7
	v_mov_b32_e32 v7, v10
	v_mov_b32_e32 v112, v15
	v_mov_b32_e32 v115, v18
	v_mov_b32_e32 v116, v27
	s_branch .LBB0_2880

; __device__ __forceinline__ void ln_load(f32x4 (&v)[8], const float* z, int lane) {
; #pragma unroll
;     for (int j = 0; j < 8; ++j) v[j] = ((const f32x4*)z)[lane + 64 * j];
; }
.LBB0_2880:
	s_add_i32 s8, s12, s2
	s_add_i32 s10, s8, 16
	s_cmpk_gt_i32 s10, 0x400f
	s_cbranch_scc1 .LBB0_2882
	s_ashr_i32 s9, s8, 31
	s_lshl_b64 s[0:1], s[8:9], 13
	s_waitcnt vmcnt(0)
	v_lshl_add_u64 v[48:49], v[76:77], 0, s[0:1]
	v_add_co_u32_e32 v120, vcc, 0x1000, v48
	flat_load_dwordx4 v[44:47], v[48:49] nt
	flat_load_dwordx4 v[40:43], v[48:49] offset:1024 nt
	flat_load_dwordx4 v[36:39], v[48:49] offset:2048 nt
	flat_load_dwordx4 v[32:35], v[48:49] offset:3072 nt
	v_addc_co_u32_e32 v121, vcc, 0, v49, vcc
	flat_load_dwordx4 v[60:63], v[120:121] nt
	flat_load_dwordx4 v[56:59], v[120:121] offset:1024 nt
	flat_load_dwordx4 v[52:55], v[120:121] offset:2048 nt
	flat_load_dwordx4 v[48:51], v[120:121] offset:3072 nt

; __device__ __forceinline__ void ln_load(f32x4 (&v)[8], const float* z, int lane) {
; #pragma unroll
;     for (int j = 0; j < 8; ++j) v[j] = ((const f32x4*)z)[lane + 64 * j];
; }
.LBB0_2884:
	s_cmpk_gt_i32 s10, 0x400f
	s_mov_b64 s[10:11], -1
	s_cbranch_scc1 .LBB0_2879
	s_add_i32 s2, s14, s2
	s_add_i32 s3, s2, 16
	s_cmpk_gt_i32 s3, 0x400f
	s_cselect_b64 s[10:11], -1, 0
	s_and_b64 vcc, exec, s[10:11]
	s_cbranch_vccnz .LBB0_2887
	s_ashr_i32 s3, s2, 31
	s_lshl_b64 s[16:17], s[2:3], 13
	v_lshl_add_u64 v[110:111], v[76:77], 0, s[16:17]
	v_add_co_u32_e32 v112, vcc, 0x1000, v110
	flat_load_dwordx4 v[0:3], v[110:111] nt
	flat_load_dwordx4 v[4:7], v[110:111] offset:1024 nt
	s_waitcnt lgkmcnt(0)
	flat_load_dwordx4 v[8:11], v[110:111] offset:2048 nt
	v_addc_co_u32_e32 v113, vcc, 0, v111, vcc
	flat_load_dwordx4 v[12:15], v[112:113] nt
	flat_load_dwordx4 v[16:19], v[112:113] offset:1024 nt
	flat_load_dwordx4 v[20:23], v[112:113] offset:2048 nt
	flat_load_dwordx4 v[24:27], v[112:113] offset:3072 nt
	flat_load_dwordx4 v[28:31], v[110:111] offset:3072 nt
	s_waitcnt vmcnt(0)
	v_mov_b32_e32 v111, v2
	v_mov_b32_e32 v110, v6
	v_mov_b32_e32 v2, v7
	s_waitcnt lgkmcnt(0)
	v_mov_b32_e32 v7, v10
	v_mov_b32_e32 v112, v15
	v_mov_b32_e32 v115, v18
	v_mov_b32_e32 v116, v27
